# GLA pass-0 unit loop: next unit operand loads issued at the top of the current unit into spare registers (whole-unit flight time), copied into place before the U-product stage; loop-top vmcnt drains r
# speedup vs baseline: 1.0563x; 1.0033x over previous
.LBB0_572:
	v_ashrrev_i32_e32 v1, 2, v187
	s_and_b32 s6, s33, 1
	v_and_b32_e32 v1, 0xffffffc0, v1
	v_lshrrev_b32_e32 v2, 1, v187
	v_and_b32_e32 v0, 31, v187
	v_lshl_add_u32 v1, s6, 7, v1
	v_and_b32_e32 v2, 32, v2
	v_or3_b32 v10, v2, v0, v1
	v_and_b32_e32 v0, 0x80, v187
	s_add_u32 s8, s41, 0x3790000
	v_mov_b32_e32 v2, 0x4500
	v_mov_b32_e32 v3, 0x100
	v_cmp_eq_u32_e32 vcc, 0, v0
	s_addc_u32 s9, s42, 0
	v_mov_b32_e32 v109, 0
	v_cndmask_b32_e32 v108, v2, v3, vcc
	v_lshl_add_u64 v[2:3], s[8:9], 0, v[108:109]
	v_ashrrev_i32_e32 v11, 31, v10
	v_lshlrev_b32_e32 v0, 8, v187
	v_lshl_add_u64 v[2:3], v[10:11], 2, v[2:3]
	v_and_b32_e32 v108, 0x2000, v0
	v_lshl_add_u64 v[12:13], v[2:3], 0, v[108:109]
	s_movk_i32 s18, 0x1000
	v_add_co_u32_e64 v14, s[4:5], s18, v12
	v_mov_b32_e32 v0, 0x2140
	s_nop 0
	v_addc_co_u32_e64 v15, s[4:5], 0, v13, s[4:5]
	global_load_dword v2, v[12:13], off
	global_load_dword v3, v[12:13], off offset:1024
	global_load_dword v4, v[12:13], off offset:2048
	global_load_dword v5, v[12:13], off offset:3072
	global_load_dword v6, v[14:15], off
	global_load_dword v7, v[14:15], off offset:1024
	global_load_dword v8, v[14:15], off offset:2048
	global_load_dword v9, v[14:15], off offset:3072
	v_mov_b32_e32 v11, 0x1040
	v_cndmask_b32_e32 v0, v0, v11, vcc
	v_add_u32_e32 v10, v10, v0
	v_ashrrev_i32_e32 v11, 31, v10
	v_lshl_add_u64 v[10:11], v[10:11], 2, s[8:9]
	global_load_dword v0, v[10:11], off
	s_load_dwordx2 s[4:5], s[0:1], 0xa0
	s_cmpk_lt_i32 s33, 0x600
	s_waitcnt lgkmcnt(0)
	v_mov_b32_e32 v10, s5
	v_mov_b32_e32 v11, s4
	s_nop 0
	v_readfirstlane_b32 s8, v11
	v_readfirstlane_b32 s9, v10
	s_cbranch_scc0 .LBB0_591
	s_lshl_b32 s4, s33, 5
	v_lshrrev_b32_e32 v11, 2, v187
	s_and_b32 s7, s4, 0xffffffc0
	v_and_or_b32 v12, v11, 48, s7
	s_add_u32 s10, s41, 0xf800000
	v_ashrrev_i32_e32 v13, 31, v12
	s_addc_u32 s11, s42, 0
	v_and_or_b32 v10, v187, 63, v1
	v_lshlrev_b64 v[12:13], 9, v[12:13]
	v_lshl_add_u64 v[12:13], s[10:11], 0, v[12:13]
	v_ashrrev_i32_e32 v11, 31, v10
	v_lshl_add_u64 v[10:11], v[10:11], 1, v[12:13]
	global_load_ushort v1, v[10:11], off
	global_load_ushort v16, v[10:11], off offset:512
	global_load_ushort v17, v[10:11], off offset:1024
	global_load_ushort v18, v[10:11], off offset:1536
	global_load_ushort v19, v[10:11], off offset:2048
	global_load_ushort v20, v[10:11], off offset:2560
	global_load_ushort v21, v[10:11], off offset:3072
	global_load_ushort v22, v[10:11], off offset:3584
	v_add_co_u32_e32 v10, vcc, s18, v10
	s_add_u32 s19, s41, 0x11000000
	s_nop 0
	v_addc_co_u32_e32 v11, vcc, 0, v11, vcc
	global_load_ushort v23, v[10:11], off
	global_load_ushort v24, v[10:11], off offset:512
	global_load_ushort v25, v[10:11], off offset:1024
	global_load_ushort v26, v[10:11], off offset:1536
	global_load_ushort v27, v[10:11], off offset:2048
	global_load_ushort v28, v[10:11], off offset:2560
	global_load_ushort v29, v[10:11], off offset:3072
	global_load_ushort v30, v[10:11], off offset:3584
	v_ashrrev_i32_e32 v10, 3, v187
	s_addc_u32 s20, s42, 0
	v_add_u32_e32 v10, s7, v10
	s_add_u32 s12, s41, 0x17000000
	v_ashrrev_i32_e32 v11, 31, v10
	s_addc_u32 s13, s42, 0
	v_lshlrev_b64 v[10:11], 7, v[10:11]
	v_lshlrev_b32_e32 v12, 4, v187
	s_lshl_b32 s4, s6, 9
	v_ashrrev_i32_e32 v14, 5, v187
	v_lshl_add_u64 v[10:11], s[12:13], 0, v[10:11]
	v_and_b32_e32 v108, 0x70, v12
	s_add_u32 s4, s19, s4
	v_add_u32_e32 v14, s7, v14
	v_lshl_add_u64 v[10:11], v[10:11], 0, v[108:109]
	s_addc_u32 s5, s20, 0
	v_and_b32_e32 v108, 0x1f0, v12
	v_ashrrev_i32_e32 v15, 31, v14
	v_lshl_add_u64 v[12:13], s[4:5], 0, v[108:109]
	v_lshlrev_b64 v[14:15], 10, v[14:15]
	v_lshl_add_u64 v[14:15], v[12:13], 0, v[14:15]
	global_load_dwordx4 v[88:91], v[10:11], off
	global_load_dwordx4 v[92:95], v[14:15], off
	v_add_u32_e32 v10, 0x200, v187
	v_ashrrev_i32_e32 v10, 5, v10
	v_add_u32_e32 v14, 0x400, v187
	v_add_u32_e32 v10, s7, v10
	v_ashrrev_i32_e32 v14, 5, v14
	v_ashrrev_i32_e32 v11, 31, v10
	v_add_u32_e32 v14, s7, v14
	v_lshlrev_b64 v[10:11], 10, v[10:11]
	v_ashrrev_i32_e32 v15, 31, v14
	v_lshl_add_u64 v[10:11], v[12:13], 0, v[10:11]
	v_lshlrev_b64 v[14:15], 10, v[14:15]
	v_lshl_add_u64 v[14:15], v[12:13], 0, v[14:15]
	global_load_dwordx4 v[96:99], v[10:11], off
	global_load_dwordx4 v[100:103], v[14:15], off
	v_add_u32_e32 v10, 0x600, v187
	v_ashrrev_i32_e32 v10, 5, v10
	v_add_u32_e32 v10, s7, v10
	v_ashrrev_i32_e32 v11, 31, v10
	v_lshlrev_b64 v[10:11], 10, v[10:11]
	v_lshl_add_u64 v[10:11], v[12:13], 0, v[10:11]
	global_load_dwordx4 v[104:107], v[10:11], off
	s_waitcnt vmcnt(28)
	v_cvt_pk_bf16_f32 v10, v3, 0
	v_lshlrev_b32_e32 v11, 16, v10
	s_waitcnt vmcnt(26)
	v_cvt_pk_bf16_f32 v12, v5, 0
	v_lshlrev_b32_e32 v13, 16, v12
	s_waitcnt vmcnt(24)
	v_cvt_pk_bf16_f32 v14, v7, 0
	v_lshlrev_b32_e32 v15, 16, v14
	s_add_u32 s14, s41, 0x3600000
	v_cvt_pk_bf16_f32 v80, v2, v3
	v_cvt_pk_bf16_f32 v81, v4, v5
	v_cvt_pk_bf16_f32 v82, v6, v7
	s_waitcnt vmcnt(22)
	v_cvt_pk_bf16_f32 v83, v8, v9
	s_addc_u32 s15, s42, 0
	s_lshl_b32 s21, s33, 1
	s_lshl_b32 s26, s40, 1
	s_movk_i32 s27, 0x220
	s_movk_i32 s28, 0x90
	s_waitcnt vmcnt(20)
	v_and_b32_e32 v110, 0xffff, v1
	v_cvt_pk_bf16_f32 v1, v2, 0
	v_lshlrev_b32_e32 v10, 16, v1
	v_cvt_pk_bf16_f32 v1, v4, 0
	v_lshlrev_b32_e32 v12, 16, v1
	v_cvt_pk_bf16_f32 v1, v6, 0
	s_waitcnt vmcnt(19)
	v_and_b32_e32 v111, 0xffff, v16
	v_lshlrev_b32_e32 v14, 16, v1
	v_cvt_pk_bf16_f32 v1, v8, 0
	v_cvt_pk_bf16_f32 v16, v9, 0
	s_waitcnt vmcnt(18)
	v_and_b32_e32 v112, 0xffff, v17
	v_lshlrev_b32_e32 v17, 16, v16
	v_lshlrev_b32_e32 v16, 16, v1
	v_pk_add_f32 v[10:11], v[2:3], v[10:11] neg_lo:[0,1] neg_hi:[0,1]
	v_pk_add_f32 v[12:13], v[4:5], v[12:13] neg_lo:[0,1] neg_hi:[0,1]
	v_pk_add_f32 v[14:15], v[6:7], v[14:15] neg_lo:[0,1] neg_hi:[0,1]
	v_pk_add_f32 v[16:17], v[8:9], v[16:17] neg_lo:[0,1] neg_hi:[0,1]
	s_waitcnt vmcnt(17)
	v_and_b32_e32 v113, 0xffff, v18
	s_waitcnt vmcnt(16)
	v_and_b32_e32 v114, 0xffff, v19
	s_waitcnt vmcnt(15)
	v_and_b32_e32 v115, 0xffff, v20
	s_waitcnt vmcnt(14)
	v_and_b32_e32 v116, 0xffff, v21
	s_waitcnt vmcnt(13)
	v_and_b32_e32 v117, 0xffff, v22
	s_waitcnt vmcnt(12)
	v_and_b32_e32 v118, 0xffff, v23
	s_waitcnt vmcnt(11)
	v_and_b32_e32 v119, 0xffff, v24
	s_waitcnt vmcnt(10)
	v_and_b32_e32 v120, 0xffff, v25
	s_waitcnt vmcnt(9)
	v_and_b32_e32 v121, 0xffff, v26
	s_waitcnt vmcnt(8)
	v_and_b32_e32 v122, 0xffff, v27
	s_waitcnt vmcnt(7)
	v_and_b32_e32 v123, 0xffff, v28
	s_waitcnt vmcnt(6)
	v_and_b32_e32 v124, 0xffff, v29
	s_waitcnt vmcnt(5)
	v_and_b32_e32 v125, 0xffff, v30
	v_cvt_pk_bf16_f32 v84, v10, v11
	v_cvt_pk_bf16_f32 v85, v12, v13
	v_cvt_pk_bf16_f32 v86, v14, v15
	v_cvt_pk_bf16_f32 v87, v16, v17
	v_mov_b32_e32 v1, v0
	v_mov_b32_e32 v2, v0
	v_mov_b32_e32 v3, v0
	v_mov_b32_e32 v4, v0
	v_mov_b32_e32 v5, v0
	v_mov_b32_e32 v6, v0
	v_mov_b32_e32 v7, v0
	v_mov_b32_e32 v8, v0
	v_mov_b32_e32 v9, v0
	v_mov_b32_e32 v10, v0
	v_mov_b32_e32 v11, v0
	v_mov_b32_e32 v12, v0
	v_mov_b32_e32 v13, v0
	v_mov_b32_e32 v14, v0
	v_mov_b32_e32 v15, v0
	s_waitcnt vmcnt(0)
	s_branch .LBB0_575

.LBB0_575:
	v_mov_b32_e32 v54, v187
	s_nop 0
	v_lshlrev_b32_e32 v16, 4, v54
	v_and_b32_e32 v17, 0xffffff80, v16
	v_and_b32_e32 v34, 0x70, v16
	v_and_b32_e32 v32, 0x1f0, v16
	v_add3_u32 v17, 0, v17, v34
	v_add_u32_e32 v16, 0, v32
	v_ashrrev_i32_e32 v61, 5, v54
	ds_write_b128 v17, v[88:91]
	v_mad_u64_u32 v[18:19], s[4:5], v61, s27, v[16:17]
	v_add_u32_e32 v17, 0x200, v54
	v_ashrrev_i32_e32 v60, 5, v17
	ds_write_b128 v18, v[92:95] offset:12288
	v_mad_u64_u32 v[18:19], s[4:5], v60, s27, v[16:17]
	v_add_u32_e32 v17, 0x400, v54
	v_ashrrev_i32_e32 v59, 5, v17
	ds_write_b128 v18, v[96:99] offset:12288
	v_mad_u64_u32 v[18:19], s[4:5], v59, s27, v[16:17]
	v_add_u32_e32 v17, 0x600, v54
	v_ashrrev_i32_e32 v57, 5, v17
	v_bfe_u32 v126, v54, 7, 1
	v_and_b32_e32 v55, 31, v54
	v_mad_u64_u32 v[16:17], s[4:5], v57, s27, v[16:17]
	v_lshlrev_b32_e32 v35, 6, v126
	ds_write_b128 v18, v[100:103] offset:12288
	ds_write_b128 v16, v[104:107] offset:12288
	s_add_i32 s88, s33, s40
	s_cmpk_lt_i32 s88, 0x600
	s_cbranch_scc0 .Lgla0_nopf
	v_mov_b32_e32 v171, 0
	v_and_b32_e32 v172, 63, v54
	v_mov_b32_e32 v204, v32
	v_mov_b32_e32 v206, v34
	s_lshl_b32 s91, s88, 5
	v_ashrrev_i32_e32 v190, 2, v54
	v_lshrrev_b32_e32 v189, 2, v54
	s_and_b32 s90, s88, 1
	s_and_b32 s88, s91, 0x7fffffc0
	v_and_b32_e32 v190, 0xffffffc0, v190
	v_lshl_add_u32 v190, s90, 7, v190
	v_and_or_b32 v170, v189, 48, s88
	v_or_b32_e32 v190, v190, v172
	v_lshlrev_b64 v[192:193], 9, v[170:171]
	v_lshl_add_u64 v[192:193], s[10:11], 0, v[192:193]
	v_ashrrev_i32_e32 v191, 31, v190
	s_lshl_b32 s90, s90, 9
	v_lshl_add_u64 v[190:191], v[190:191], 1, v[192:193]
	s_add_u32 s90, s19, s90
	v_add_u32_e32 v196, s88, v60
	global_load_ushort v189, v[190:191], off
	global_load_ushort v200, v[190:191], off offset:512
	global_load_ushort v201, v[190:191], off offset:1024
	global_load_ushort v202, v[190:191], off offset:1536
	global_load_ushort v203, v[190:191], off offset:2048
	global_load_ushort v209, v[190:191], off offset:2560
	global_load_ushort v210, v[190:191], off offset:3072
	global_load_ushort v211, v[190:191], off offset:3584
	v_add_co_u32_e32 v190, vcc, s18, v190
	s_addc_u32 s91, s20, 0
	v_mov_b32_e32 v205, v171
	v_ashrrev_i32_e32 v197, 31, v196
	v_add_u32_e32 v198, s88, v59
	v_addc_co_u32_e32 v191, vcc, 0, v191, vcc
	v_lshl_add_u64 v[192:193], s[90:91], 0, v[204:205]
	v_lshlrev_b64 v[196:197], 10, v[196:197]
	v_ashrrev_i32_e32 v199, 31, v198
	global_load_ushort v212, v[190:191], off
	global_load_ushort v213, v[190:191], off offset:512
	global_load_ushort v214, v[190:191], off offset:1024
	global_load_ushort v215, v[190:191], off offset:1536
	global_load_ushort v216, v[190:191], off offset:2048
	global_load_ushort v217, v[190:191], off offset:2560
	global_load_ushort v218, v[190:191], off offset:3072
	global_load_ushort v219, v[190:191], off offset:3584
	v_ashrrev_i32_e32 v190, 3, v54
	v_lshl_add_u64 v[196:197], v[192:193], 0, v[196:197]
	v_lshlrev_b64 v[198:199], 10, v[198:199]
	v_add_u32_e32 v190, s88, v190
	v_add_u32_e32 v194, s88, v61
	v_lshl_add_u64 v[198:199], v[192:193], 0, v[198:199]
	global_load_dwordx4 v[228:231], v[196:197], off
	global_load_dwordx4 v[232:235], v[198:199], off
	v_add_u32_e32 v196, s88, v57
	v_ashrrev_i32_e32 v191, 31, v190
	v_ashrrev_i32_e32 v195, 31, v194
	v_ashrrev_i32_e32 v197, 31, v196
	v_lshlrev_b64 v[190:191], 7, v[190:191]
	v_lshlrev_b64 v[194:195], 10, v[194:195]
	v_lshlrev_b64 v[196:197], 10, v[196:197]
	v_lshl_add_u64 v[190:191], s[12:13], 0, v[190:191]
	v_mov_b32_e32 v207, v171
	v_lshl_add_u64 v[194:195], v[192:193], 0, v[194:195]
	v_lshl_add_u64 v[192:193], v[192:193], 0, v[196:197]
	v_lshl_add_u64 v[190:191], v[190:191], 0, v[206:207]
	global_load_dwordx4 v[236:239], v[192:193], off
	global_load_dwordx4 v[220:223], v[190:191], off
	global_load_dwordx4 v[224:227], v[194:195], off
.Lgla0_nopf:
	v_and_b32_e32 v16, 32, v54
	v_add_u32_e32 v17, 0, v35
	v_lshlrev_b32_e32 v18, 7, v55
	v_add3_u32 v48, v17, v16, v18
	s_waitcnt lgkmcnt(0)
	s_barrier
	ds_read_b128 v[16:19], v48
	ds_read_b128 v[20:23], v48 offset:16
	v_bfe_u32 v56, v54, 5, 1
	v_ashrrev_i32_e32 v33, 8, v54
	v_ashrrev_i32_e32 v49, 6, v54
	s_waitcnt lgkmcnt(1)
	v_cvt_pk_bf16_f32 v26, v18, 0
	v_cvt_pk_bf16_f32 v27, v19, 0
	v_lshlrev_b32_e32 v26, 16, v26
	v_lshlrev_b32_e32 v27, 16, v27
	v_cvt_pk_bf16_f32 v36, v16, v17
	v_cvt_pk_bf16_f32 v37, v18, v19
	s_waitcnt lgkmcnt(0)
	v_cvt_pk_bf16_f32 v38, v20, v21
	v_cvt_pk_bf16_f32 v39, v22, v23
	v_pk_add_f32 v[42:43], v[18:19], v[26:27] neg_lo:[0,1] neg_hi:[0,1]
	v_cvt_pk_bf16_f32 v26, v20, 0
	v_cvt_pk_bf16_f32 v27, v21, 0
	v_cvt_pk_bf16_f32 v24, v16, 0
	v_cvt_pk_bf16_f32 v25, v17, 0
	v_lshlrev_b32_e32 v27, 16, v27
	v_lshlrev_b32_e32 v26, 16, v26
	v_lshlrev_b32_e32 v25, 16, v25
	v_lshlrev_b32_e32 v24, 16, v24
	v_pk_add_f32 v[44:45], v[20:21], v[26:27] neg_lo:[0,1] neg_hi:[0,1]
	v_cvt_pk_bf16_f32 v26, v22, 0
	v_cvt_pk_bf16_f32 v27, v23, 0
	v_pk_add_f32 v[24:25], v[16:17], v[24:25] neg_lo:[0,1] neg_hi:[0,1]
	v_lshlrev_b32_e32 v16, 16, v26
	v_lshlrev_b32_e32 v17, 16, v27
	v_pk_add_f32 v[46:47], v[22:23], v[16:17] neg_lo:[0,1] neg_hi:[0,1]
	v_cvt_pk_bf16_f32 v40, v24, v25
	v_mfma_f32_32x32x16_bf16 v[16:31], v[36:39], v[80:83], v[0:15]
	v_cvt_pk_bf16_f32 v41, v42, v43
	v_cvt_pk_bf16_f32 v42, v44, v45
	v_cvt_pk_bf16_f32 v43, v46, v47
	v_lshlrev_b32_e32 v58, 7, v33
	v_and_b32_e32 v127, 1, v49
	v_and_b32_e32 v128, 63, v54
	v_and_b32_e32 v63, 3, v49
	v_mfma_f32_32x32x16_bf16 v[16:31], v[40:43], v[80:83], v[16:31]
	v_lshlrev_b32_e32 v40, 2, v56
	v_or3_b32 v35, v40, v58, v35
	v_lshlrev_b32_e32 v35, 8, v35
	v_cmp_eq_u32_e32 vcc, 0, v63
	v_cmp_ne_u32_e64 s[4:5], 0, v63
	v_mfma_f32_32x32x16_bf16 v[16:31], v[36:39], v[84:87], v[16:31]
	v_lshl_add_u32 v37, v127, 7, 0
	v_lshlrev_b32_e32 v38, 2, v55
	v_add3_u32 v35, v37, v38, v35
	s_nop 8
	v_mul_f32_e32 v16, 0x3fb8aa3b, v16
	v_exp_f32_e64 v36, -|v16|
	v_mul_f32_e32 v17, 0x3fb8aa3b, v17
	v_exp_f32_e64 v39, -|v17|
	v_min_f32_e32 v16, 0, v16
	v_add_f32_e32 v36, 1.0, v36
	v_log_f32_e32 v36, v36
	v_min_f32_e32 v17, 0, v17
	v_mul_f32_e32 v18, 0x3fb8aa3b, v18
	v_sub_f32_e32 v16, v16, v36
	v_add_f32_e32 v36, 1.0, v39
	v_log_f32_e32 v36, v36
	v_mul_f32_e32 v16, 0x3d800000, v16
	v_sub_f32_e32 v17, v17, v36
	v_mul_f32_e32 v17, 0x3d800000, v17
	ds_write2st64_b32 v35, v16, v17 offset0:184 offset1:185
	v_mul_f32_e32 v16, 0x3fb8aa3b, v19
	v_exp_f32_e64 v36, -|v18|
	v_exp_f32_e64 v17, -|v16|
	v_min_f32_e32 v18, 0, v18
	v_min_f32_e32 v16, 0, v16
	v_add_f32_e32 v19, 1.0, v36
	v_add_f32_e32 v17, 1.0, v17
	v_log_f32_e32 v19, v19
	v_log_f32_e32 v17, v17
	v_sub_f32_e32 v18, v18, v19
	v_sub_f32_e32 v16, v16, v17
	v_mul_f32_e32 v18, 0x3d800000, v18
	v_mul_f32_e32 v16, 0x3d800000, v16
	v_mul_f32_e32 v17, 0x3fb8aa3b, v20
	ds_write2st64_b32 v35, v18, v16 offset0:186 offset1:187
	v_mul_f32_e32 v16, 0x3fb8aa3b, v21
	v_exp_f32_e64 v19, -|v17|
	v_exp_f32_e64 v18, -|v16|
	v_min_f32_e32 v17, 0, v17
	v_min_f32_e32 v16, 0, v16
	v_add_f32_e32 v19, 1.0, v19
	v_add_f32_e32 v18, 1.0, v18
	v_log_f32_e32 v19, v19
	v_log_f32_e32 v18, v18
	v_sub_f32_e32 v17, v17, v19
	v_sub_f32_e32 v16, v16, v18
	v_mul_f32_e32 v17, 0x3d800000, v17
	v_mul_f32_e32 v16, 0x3d800000, v16
	v_mul_f32_e32 v18, 0x3fb8aa3b, v22
	ds_write2st64_b32 v35, v17, v16 offset0:192 offset1:193
	v_mul_f32_e32 v16, 0x3fb8aa3b, v23
	v_exp_f32_e64 v19, -|v18|
	v_exp_f32_e64 v17, -|v16|
	v_min_f32_e32 v18, 0, v18
	v_min_f32_e32 v16, 0, v16
	v_add_f32_e32 v19, 1.0, v19
	v_add_f32_e32 v17, 1.0, v17
	v_log_f32_e32 v19, v19
	v_log_f32_e32 v17, v17
	v_sub_f32_e32 v18, v18, v19
	v_sub_f32_e32 v16, v16, v17
	v_mul_f32_e32 v18, 0x3d800000, v18
	v_mul_f32_e32 v16, 0x3d800000, v16
	v_mul_f32_e32 v17, 0x3fb8aa3b, v24
	ds_write2st64_b32 v35, v18, v16 offset0:194 offset1:195
	v_mul_f32_e32 v16, 0x3fb8aa3b, v25
	v_exp_f32_e64 v19, -|v17|
	v_exp_f32_e64 v18, -|v16|
	v_min_f32_e32 v17, 0, v17
	v_min_f32_e32 v16, 0, v16
	v_add_f32_e32 v19, 1.0, v19
	v_add_f32_e32 v18, 1.0, v18
	v_log_f32_e32 v19, v19
	v_log_f32_e32 v18, v18
	v_sub_f32_e32 v17, v17, v19
	v_sub_f32_e32 v16, v16, v18
	v_mul_f32_e32 v17, 0x3d800000, v17
	v_mul_f32_e32 v16, 0x3d800000, v16
	v_mul_f32_e32 v18, 0x3fb8aa3b, v26
	ds_write2st64_b32 v35, v17, v16 offset0:200 offset1:201
	v_mul_f32_e32 v16, 0x3fb8aa3b, v27
	v_exp_f32_e64 v19, -|v18|
	v_exp_f32_e64 v17, -|v16|
	v_min_f32_e32 v18, 0, v18
	v_min_f32_e32 v16, 0, v16
	v_add_f32_e32 v19, 1.0, v19
	v_add_f32_e32 v17, 1.0, v17
	v_log_f32_e32 v19, v19
	v_log_f32_e32 v17, v17
	v_sub_f32_e32 v18, v18, v19
	v_sub_f32_e32 v16, v16, v17
	v_mul_f32_e32 v18, 0x3d800000, v18
	v_mul_f32_e32 v16, 0x3d800000, v16
	v_mul_f32_e32 v17, 0x3fb8aa3b, v28
	ds_write2st64_b32 v35, v18, v16 offset0:202 offset1:203
	v_mul_f32_e32 v16, 0x3fb8aa3b, v29
	v_exp_f32_e64 v19, -|v17|
	v_exp_f32_e64 v18, -|v16|
	v_min_f32_e32 v17, 0, v17
	v_min_f32_e32 v16, 0, v16
	v_add_f32_e32 v19, 1.0, v19
	v_add_f32_e32 v18, 1.0, v18
	v_log_f32_e32 v19, v19
	v_log_f32_e32 v18, v18
	v_sub_f32_e32 v17, v17, v19
	v_sub_f32_e32 v16, v16, v18
	v_mul_f32_e32 v17, 0x3d800000, v17
	v_mul_f32_e32 v16, 0x3d800000, v16
	v_mul_f32_e32 v18, 0x3fb8aa3b, v30
	ds_write2st64_b32 v35, v17, v16 offset0:208 offset1:209
	v_mul_f32_e32 v16, 0x3fb8aa3b, v31
	v_exp_f32_e64 v19, -|v18|
	v_exp_f32_e64 v17, -|v16|
	v_min_f32_e32 v18, 0, v18
	v_min_f32_e32 v16, 0, v16
	v_add_f32_e32 v19, 1.0, v19
	v_add_f32_e32 v17, 1.0, v17
	v_log_f32_e32 v19, v19
	v_log_f32_e32 v17, v17
	v_sub_f32_e32 v18, v18, v19
	v_sub_f32_e32 v16, v16, v17
	v_mul_f32_e32 v18, 0x3d800000, v18
	v_mul_f32_e32 v16, 0x3d800000, v16
	ds_write2st64_b32 v35, v18, v16 offset0:210 offset1:211
	ds_read_b128 v[16:19], v48 offset:4096
	ds_read_b128 v[20:23], v48 offset:4112
	s_waitcnt lgkmcnt(1)
	v_cvt_pk_bf16_f32 v26, v18, 0
	v_cvt_pk_bf16_f32 v27, v19, 0
	v_lshlrev_b32_e32 v26, 16, v26
	v_lshlrev_b32_e32 v27, 16, v27
	v_cvt_pk_bf16_f32 v36, v16, v17
	v_cvt_pk_bf16_f32 v37, v18, v19
	s_waitcnt lgkmcnt(0)
	v_cvt_pk_bf16_f32 v38, v20, v21
	v_cvt_pk_bf16_f32 v39, v22, v23
	v_pk_add_f32 v[42:43], v[18:19], v[26:27] neg_lo:[0,1] neg_hi:[0,1]
	v_cvt_pk_bf16_f32 v26, v20, 0
	v_cvt_pk_bf16_f32 v27, v21, 0
	v_cvt_pk_bf16_f32 v24, v16, 0
	v_cvt_pk_bf16_f32 v25, v17, 0
	v_lshlrev_b32_e32 v27, 16, v27
	v_lshlrev_b32_e32 v26, 16, v26
	v_lshlrev_b32_e32 v25, 16, v25
	v_lshlrev_b32_e32 v24, 16, v24
	v_pk_add_f32 v[44:45], v[20:21], v[26:27] neg_lo:[0,1] neg_hi:[0,1]
	v_cvt_pk_bf16_f32 v26, v22, 0
	v_cvt_pk_bf16_f32 v27, v23, 0
	v_pk_add_f32 v[24:25], v[16:17], v[24:25] neg_lo:[0,1] neg_hi:[0,1]
	v_lshlrev_b32_e32 v16, 16, v26
	v_lshlrev_b32_e32 v17, 16, v27
	v_pk_add_f32 v[46:47], v[22:23], v[16:17] neg_lo:[0,1] neg_hi:[0,1]
	v_cvt_pk_bf16_f32 v40, v24, v25
	v_mfma_f32_32x32x16_bf16 v[16:31], v[36:39], v[80:83], v[0:15]
	v_cvt_pk_bf16_f32 v41, v42, v43
	v_cvt_pk_bf16_f32 v42, v44, v45
	v_cvt_pk_bf16_f32 v43, v46, v47
	v_lshl_add_u32 v46, v128, 2, 0
	s_nop 0
	v_mfma_f32_32x32x16_bf16 v[16:31], v[40:43], v[80:83], v[16:31]
	v_mfma_f32_32x32x16_bf16 v[16:31], v[36:39], v[84:87], v[16:31]
	s_nop 11
	v_mul_f32_e32 v16, 0x3fb8aa3b, v16
	v_mul_f32_e32 v17, 0x3fb8aa3b, v17
	v_exp_f32_e64 v36, -|v16|
	v_exp_f32_e64 v37, -|v17|
	v_min_f32_e32 v16, 0, v16
	v_min_f32_e32 v17, 0, v17
	v_add_f32_e32 v36, 1.0, v36
	v_add_f32_e32 v37, 1.0, v37
	v_log_f32_e32 v36, v36
	v_log_f32_e32 v37, v37
	v_mul_f32_e32 v18, 0x3fb8aa3b, v18
	v_sub_f32_e32 v16, v16, v36
	v_sub_f32_e32 v17, v17, v37
	v_mul_f32_e32 v16, 0x3d800000, v16
	v_mul_f32_e32 v17, 0x3d800000, v17
	ds_write2st64_b32 v35, v16, v17 offset0:216 offset1:217
	v_mul_f32_e32 v16, 0x3fb8aa3b, v19
	v_exp_f32_e64 v36, -|v18|
	v_exp_f32_e64 v17, -|v16|
	v_min_f32_e32 v18, 0, v18
	v_min_f32_e32 v16, 0, v16
	v_add_f32_e32 v19, 1.0, v36
	v_add_f32_e32 v17, 1.0, v17
	v_log_f32_e32 v19, v19
	v_log_f32_e32 v17, v17
	v_sub_f32_e32 v18, v18, v19
	v_sub_f32_e32 v16, v16, v17
	v_mul_f32_e32 v18, 0x3d800000, v18
	v_mul_f32_e32 v16, 0x3d800000, v16
	v_mul_f32_e32 v17, 0x3fb8aa3b, v20
	ds_write2st64_b32 v35, v18, v16 offset0:218 offset1:219
	v_mul_f32_e32 v16, 0x3fb8aa3b, v21
	v_exp_f32_e64 v19, -|v17|
	v_exp_f32_e64 v18, -|v16|
	v_min_f32_e32 v17, 0, v17
	v_min_f32_e32 v16, 0, v16
	v_add_f32_e32 v19, 1.0, v19
	v_add_f32_e32 v18, 1.0, v18
	v_log_f32_e32 v19, v19
	v_log_f32_e32 v18, v18
	v_sub_f32_e32 v17, v17, v19
	v_sub_f32_e32 v16, v16, v18
	v_mul_f32_e32 v17, 0x3d800000, v17
	v_mul_f32_e32 v16, 0x3d800000, v16
	v_mul_f32_e32 v18, 0x3fb8aa3b, v22
	ds_write2st64_b32 v35, v17, v16 offset0:224 offset1:225
	v_mul_f32_e32 v16, 0x3fb8aa3b, v23
	v_exp_f32_e64 v19, -|v18|
	v_exp_f32_e64 v17, -|v16|
	v_min_f32_e32 v18, 0, v18
	v_min_f32_e32 v16, 0, v16
	v_add_f32_e32 v19, 1.0, v19
	v_add_f32_e32 v17, 1.0, v17
	v_log_f32_e32 v19, v19
	v_log_f32_e32 v17, v17
	v_sub_f32_e32 v18, v18, v19
	v_sub_f32_e32 v16, v16, v17
	v_mul_f32_e32 v18, 0x3d800000, v18
	v_mul_f32_e32 v16, 0x3d800000, v16
	v_mul_f32_e32 v17, 0x3fb8aa3b, v24
	ds_write2st64_b32 v35, v18, v16 offset0:226 offset1:227
	v_mul_f32_e32 v16, 0x3fb8aa3b, v25
	v_exp_f32_e64 v19, -|v17|
	v_exp_f32_e64 v18, -|v16|
	v_min_f32_e32 v17, 0, v17
	v_min_f32_e32 v16, 0, v16
	v_add_f32_e32 v19, 1.0, v19
	v_add_f32_e32 v18, 1.0, v18
	v_log_f32_e32 v19, v19
	v_log_f32_e32 v18, v18
	v_sub_f32_e32 v17, v17, v19
	v_sub_f32_e32 v16, v16, v18
	v_mul_f32_e32 v17, 0x3d800000, v17
	v_mul_f32_e32 v16, 0x3d800000, v16
	v_mul_f32_e32 v18, 0x3fb8aa3b, v26
	ds_write2st64_b32 v35, v17, v16 offset0:232 offset1:233
	v_mul_f32_e32 v16, 0x3fb8aa3b, v27
	v_exp_f32_e64 v19, -|v18|
	v_exp_f32_e64 v17, -|v16|
	v_min_f32_e32 v18, 0, v18
	v_min_f32_e32 v16, 0, v16
	v_add_f32_e32 v19, 1.0, v19
	v_add_f32_e32 v17, 1.0, v17
	v_log_f32_e32 v19, v19
	v_log_f32_e32 v17, v17
	v_sub_f32_e32 v18, v18, v19
	v_sub_f32_e32 v16, v16, v17
	v_mul_f32_e32 v18, 0x3d800000, v18
	v_mul_f32_e32 v16, 0x3d800000, v16
	v_mul_f32_e32 v17, 0x3fb8aa3b, v28
	ds_write2st64_b32 v35, v18, v16 offset0:234 offset1:235
	v_mul_f32_e32 v16, 0x3fb8aa3b, v29
	v_exp_f32_e64 v19, -|v17|
	v_exp_f32_e64 v18, -|v16|
	v_min_f32_e32 v17, 0, v17
	v_min_f32_e32 v16, 0, v16
	v_add_f32_e32 v19, 1.0, v19
	v_add_f32_e32 v18, 1.0, v18
	v_log_f32_e32 v19, v19
	v_log_f32_e32 v18, v18
	v_sub_f32_e32 v17, v17, v19
	v_sub_f32_e32 v16, v16, v18
	v_mul_f32_e32 v17, 0x3d800000, v17
	v_mul_f32_e32 v16, 0x3d800000, v16
	v_mul_f32_e32 v18, 0x3fb8aa3b, v30
	ds_write2st64_b32 v35, v17, v16 offset0:240 offset1:241
	v_mul_f32_e32 v16, 0x3fb8aa3b, v31
	v_exp_f32_e64 v19, -|v18|
	v_exp_f32_e64 v17, -|v16|
	v_min_f32_e32 v18, 0, v18
	v_min_f32_e32 v16, 0, v16
	v_add_f32_e32 v19, 1.0, v19
	v_add_f32_e32 v17, 1.0, v17
	v_log_f32_e32 v19, v19
	v_log_f32_e32 v17, v17
	v_sub_f32_e32 v18, v18, v19
	v_sub_f32_e32 v16, v16, v17
	v_mul_f32_e32 v18, 0x3d800000, v18
	v_mul_f32_e32 v16, 0x3d800000, v16
	ds_write2st64_b32 v35, v18, v16 offset0:242 offset1:243
	v_lshlrev_b32_e32 v16, 12, v63
	v_lshlrev_b32_e32 v17, 15, v33
	v_add3_u32 v26, v46, v16, v17
	s_waitcnt lgkmcnt(0)
	s_barrier
	ds_read2st64_b32 v[36:37], v26 offset0:184 offset1:185
	ds_read2st64_b32 v[18:19], v26 offset0:248 offset1:249
	ds_read2st64_b32 v[38:39], v26 offset0:186 offset1:187
	ds_read2st64_b32 v[40:41], v26 offset0:188 offset1:189
	ds_read2st64_b32 v[42:43], v26 offset0:190 offset1:191
	ds_read2st64_b32 v[24:25], v26 offset0:250 offset1:251
	ds_read2st64_b32 v[20:21], v26 offset0:252 offset1:253
	ds_read2st64_b32 v[16:17], v26 offset0:254 offset1:255
	s_waitcnt lgkmcnt(7)
	v_add_f32_e32 v22, 0, v36
	s_waitcnt lgkmcnt(6)
	v_add_f32_e32 v23, 0, v18
	v_add_f32_e32 v22, v22, v37
	v_add_f32_e32 v23, v23, v19
	s_waitcnt lgkmcnt(5)
	v_add_f32_e32 v22, v22, v38
	s_waitcnt lgkmcnt(2)
	v_add_f32_e32 v23, v23, v24
	v_add_f32_e32 v22, v22, v39
	v_add_f32_e32 v23, v23, v25
	v_add_f32_e32 v22, v22, v40
	s_waitcnt lgkmcnt(1)
	v_add_f32_e32 v23, v23, v20
	v_add_f32_e32 v22, v22, v41
	v_add_f32_e32 v23, v23, v21
	v_add_f32_e32 v22, v22, v42
	s_waitcnt lgkmcnt(0)
	v_add_f32_e32 v23, v23, v16
	v_add_u32_e32 v27, 0xb800, v26
	v_add_f32_e32 v28, v22, v43
	v_add_f32_e32 v35, v23, v17
	ds_read2st64_b32 v[44:45], v26 offset0:192 offset1:193
	ds_read2st64_b32 v[22:23], v27 offset0:72 offset1:73
	ds_read2st64_b32 v[48:49], v26 offset0:194 offset1:195
	ds_read2st64_b32 v[50:51], v26 offset0:196 offset1:197
	ds_read2st64_b32 v[52:53], v26 offset0:198 offset1:199
	s_waitcnt lgkmcnt(4)
	v_add_f32_e32 v36, v28, v44
	ds_read2st64_b32 v[30:31], v27 offset0:74 offset1:75
	ds_read2st64_b32 v[28:29], v27 offset0:76 offset1:77
	ds_read2st64_b32 v[26:27], v27 offset0:78 offset1:79
	s_waitcnt lgkmcnt(6)
	v_add_f32_e32 v35, v35, v22
	v_add_f32_e32 v36, v36, v45
	v_add_f32_e32 v35, v35, v23
	s_waitcnt lgkmcnt(5)
	v_add_f32_e32 v36, v36, v48
	s_waitcnt lgkmcnt(2)
	v_add_f32_e32 v35, v35, v30
	v_add_f32_e32 v36, v36, v49
	v_add_f32_e32 v35, v35, v31
	v_add_f32_e32 v36, v36, v50
	s_waitcnt lgkmcnt(1)
	v_add_f32_e32 v35, v35, v28
	v_add_f32_e32 v36, v36, v51
	v_add_f32_e32 v35, v35, v29
	v_add_f32_e32 v36, v36, v52
	s_waitcnt lgkmcnt(0)
	v_add_f32_e32 v47, v35, v26
	v_add_f32_e32 v35, v36, v53
	v_lshlrev_b32_e32 v36, 3, v33
	v_add_f32_e32 v27, v47, v27
	v_or_b32_e32 v47, v36, v63
	v_lshl_add_u32 v47, v47, 8, v46
	ds_write_b32 v47, v35 offset:8192
	v_or_b32_e32 v47, 4, v36
	v_or_b32_e32 v36, v47, v63
	v_lshl_add_u32 v36, v36, 8, v46
	ds_write_b32 v36, v27 offset:8192
	v_mov_b32_e32 v36, 0
	s_waitcnt lgkmcnt(0)
	s_barrier
	s_and_saveexec_b64 s[6:7], s[4:5]
	s_cbranch_execz .LBB0_577
	v_lshl_add_u32 v36, v47, 8, v46
	ds_read_b32 v36, v36 offset:8192
	s_waitcnt lgkmcnt(0)
	v_add_f32_e32 v36, 0, v36

.LBB0_589:
	s_andn2_b64 vcc, exec, s[6:7]
	s_cbranch_vccnz .LBB0_574
	s_waitcnt vmcnt(0)
	v_and_b32_e32 v110, 0xffff, v189
	v_and_b32_e32 v111, 0xffff, v200
	v_and_b32_e32 v112, 0xffff, v201
	v_and_b32_e32 v113, 0xffff, v202
	v_and_b32_e32 v114, 0xffff, v203
	v_and_b32_e32 v115, 0xffff, v209
	v_and_b32_e32 v116, 0xffff, v210
	v_and_b32_e32 v117, 0xffff, v211
	v_mov_b32_e32 v17, v16
	v_and_b32_e32 v118, 0xffff, v212
	v_and_b32_e32 v119, 0xffff, v213
	v_and_b32_e32 v120, 0xffff, v214
	v_and_b32_e32 v121, 0xffff, v215
	v_and_b32_e32 v122, 0xffff, v216
	v_and_b32_e32 v123, 0xffff, v217
	v_and_b32_e32 v124, 0xffff, v218
	v_and_b32_e32 v125, 0xffff, v219
	v_mov_b32_e32 v88, v220
	v_mov_b32_e32 v89, v221
	v_mov_b32_e32 v90, v222
	v_mov_b32_e32 v91, v223
	v_mov_b32_e32 v92, v224
	v_mov_b32_e32 v93, v225
	v_mov_b32_e32 v94, v226
	v_mov_b32_e32 v95, v227
	v_mov_b32_e32 v96, v228
	v_mov_b32_e32 v97, v229
	v_mov_b32_e32 v98, v230
	v_mov_b32_e32 v99, v231
	v_mov_b32_e32 v100, v232
	v_mov_b32_e32 v101, v233
	v_mov_b32_e32 v102, v234
	v_mov_b32_e32 v103, v235
	v_mov_b32_e32 v104, v236
	v_mov_b32_e32 v105, v237
	v_mov_b32_e32 v106, v238
	v_mov_b32_e32 v107, v239
	s_branch .LBB0_574

	.amdhsa_kernel _Z9hymba_fwd6Params
		.amdhsa_group_segment_fixed_size 0
		.amdhsa_private_segment_fixed_size 0
		.amdhsa_kernarg_size 432
		.amdhsa_user_sgpr_count 2
		.amdhsa_user_sgpr_dispatch_ptr 0
		.amdhsa_user_sgpr_queue_ptr 0
		.amdhsa_user_sgpr_kernarg_segment_ptr 1
		.amdhsa_user_sgpr_dispatch_id 0
		.amdhsa_user_sgpr_kernarg_preload_length 0
		.amdhsa_user_sgpr_kernarg_preload_offset 0
		.amdhsa_user_sgpr_private_segment_size 0
		.amdhsa_uses_dynamic_stack 0
		.amdhsa_enable_private_segment 0
		.amdhsa_system_sgpr_workgroup_id_x 1
		.amdhsa_system_sgpr_workgroup_id_y 0
		.amdhsa_system_sgpr_workgroup_id_z 0
		.amdhsa_system_sgpr_workgroup_info 0
		.amdhsa_system_vgpr_workitem_id 2
		.amdhsa_next_free_vgpr 248
		.amdhsa_next_free_sgpr 92
		.amdhsa_accum_offset 248
		.amdhsa_reserve_vcc 1
		.amdhsa_float_round_mode_32 0
		.amdhsa_float_round_mode_16_64 0
		.amdhsa_float_denorm_mode_32 3
		.amdhsa_float_denorm_mode_16_64 3
		.amdhsa_dx10_clamp 1
		.amdhsa_ieee_mode 1
		.amdhsa_fp16_overflow 0
		.amdhsa_tg_split 0
		.amdhsa_exception_fp_ieee_invalid_op 0
		.amdhsa_exception_fp_denorm_src 0
		.amdhsa_exception_fp_ieee_div_zero 0
		.amdhsa_exception_fp_ieee_overflow 0
		.amdhsa_exception_fp_ieee_underflow 0
		.amdhsa_exception_fp_ieee_inexact 0
		.amdhsa_exception_int_div_zero 0
	.end_amdhsa_kernel

amdhsa.kernels:
  - .agpr_count:     0
    .args:
      - .offset:         0
        .size:           176
        .value_kind:     by_value
      - .offset:         176
        .size:           4
        .value_kind:     hidden_block_count_x
      - .offset:         180
        .size:           4
        .value_kind:     hidden_block_count_y
      - .offset:         184
        .size:           4
        .value_kind:     hidden_block_count_z
      - .offset:         188
        .size:           2
        .value_kind:     hidden_group_size_x
      - .offset:         190
        .size:           2
        .value_kind:     hidden_group_size_y
      - .offset:         192
        .size:           2
        .value_kind:     hidden_group_size_z
      - .offset:         194
        .size:           2
        .value_kind:     hidden_remainder_x
      - .offset:         196
        .size:           2
        .value_kind:     hidden_remainder_y
      - .offset:         198
        .size:           2
        .value_kind:     hidden_remainder_z
      - .offset:         216
        .size:           8
        .value_kind:     hidden_global_offset_x
      - .offset:         224
        .size:           8
        .value_kind:     hidden_global_offset_y
      - .offset:         232
        .size:           8
        .value_kind:     hidden_global_offset_z
      - .offset:         240
        .size:           2
        .value_kind:     hidden_grid_dims
      - .offset:         264
        .size:           8
        .value_kind:     hidden_multigrid_sync_arg
      - .offset:         296
        .size:           4
        .value_kind:     hidden_dynamic_lds_size
    .group_segment_fixed_size: 0
    .kernarg_segment_align: 8
    .kernarg_segment_size: 432
    .language:       OpenCL C
    .language_version:
      - 2
      - 0
    .max_flat_workgroup_size: 512
    .name:           _Z9hymba_fwd6Params
    .private_segment_fixed_size: 0
    .sgpr_count:     98
    .sgpr_spill_count: 0
    .symbol:         _Z9hymba_fwd6Params.kd
    .uniform_work_group_size: 1
    .uses_dynamic_stack: false
    .vgpr_count:     248
    .vgpr_spill_count: 0
    .wavefront_size: 64
